# one static s_setprio 1 for waves 4-7 (the lagging half) across each GEMM phase instead of per-phase flips
# baseline (speedup 1.0000x reference)
; #define PG8_STAGE(bufoff, gbase, voff) do { _Pragma("unroll") for (int _i = 0; _i < 2; ++_i) \
;         __builtin_amdgcn_global_load_lds((const unsigned*)((const char*)(gbase) + (voff)[_i]), (LAS unsigned*)(lds + (bufoff) + ldsw + _i * 8192), 16, 0, 0); } while (0)
; #define PG8_BAR __builtin_amdgcn_s_barrier()
; template <class Epi, class Sched>
; __device__ __forceinline__ void gemm_phase(LAS unsigned char* lds, const Gemm g, const Sched& S, const Epi& E) {
;     ...
;     for (int i = 0; i < 2; ++i) { int R, C; stage_rc(tid * 16 + i * 8192, R, C); const int Rb = Epi::PERM ? ((R & ~31) + perm32(R & 31)) : R;
;         voffA[i] = (unsigned)(R * K + C) * 2u; voffB[i] = (unsigned)(Rb * K + C) * 2u; }
;     const size_t kstep = (size_t)(BK * 2);
;     const size_t hstep = (size_t)HALF * K * 2;
;     const size_t tstep = 2 * hstep;
;     const unsigned ldsw = (unsigned)wid * 1024u;
;     const int aoff = lds_byte(wr * 64 + fr, fq * 8), boff = lds_byte(wc * 32 + fr, fq * 8);
;     ...
;     Unit cur, nxt; int ui = 0;
;     if (!S.next(0, cur)) return;
;     f32x4 acc[2][2][4][2];
; #pragma unroll
;     for (int a = 0; a < 2; ++a)
; #pragma unroll
;         for (int b = 0; b < 2; ++b)
; #pragma unroll
;             for (int m = 0; m < 4; ++m)
; #pragma unroll
;                 for (int n = 0; n < 2; ++n) acc[a][b][m][n] = (f32x4){0.f, 0.f, 0.f, 0.f};
;     bf16x8 At[4][2], B0[2][2], B1[2][2];
;     const char* cA = (const char*)g.A + (size_t)cur.pm * tstep; const char* cB = (const char*)g.Bt + (size_t)cur.pn * tstep;
;     S.a_ready(cur);
;     PG8_STAGE(PG8_SB(0, 0), cB, voffB); PG8_STAGE(PG8_SA(0, 0), cA, voffA); PG8_STAGE(PG8_SB(0, 1), cB + hstep, voffB); PG8_STAGE(PG8_SA(0, 1), cA + hstep, voffA);
;     if (wr == 1) PG8_BAR;
.LBB0_334:
	s_or_b64 exec, exec, s[0:1]
	v_readlane_b32 s0, v253, 26
	v_readlane_b32 s4, v251, 0
	s_mul_i32 s0, s0, 0x6400000
	v_readlane_b32 s8, v251, 4
	v_readlane_b32 s9, v251, 5
	s_add_u32 s0, s8, s0
	v_readlane_b32 s1, v253, 27
	v_writelane_b32 v254, s0, 10
	s_addc_u32 s0, s9, 0
	v_writelane_b32 v254, s0, 11
	v_readlane_b32 s0, v252, 31
	v_mov_b32_e32 v8, v170
	v_readlane_b32 s1, v252, 32
	s_waitcnt lgkmcnt(0)
	s_barrier
	s_andn2_b64 vcc, exec, s[0:1]
	v_readfirstlane_b32 s22, v8
	v_readlane_b32 s5, v251, 1
	v_readlane_b32 s6, v251, 2
	v_readlane_b32 s7, v251, 3
	v_readlane_b32 s10, v251, 6
	v_readlane_b32 s11, v251, 7
	s_cbranch_vccnz .LBB0_362
	v_lshlrev_b32_e32 v0, 4, v8
	v_add_u32_e32 v3, 0x2000, v0
	v_ashrrev_i32_e32 v2, 31, v3
	v_lshrrev_b32_e32 v2, 22, v2
	v_add_u32_e32 v2, v3, v2
	v_ashrrev_i32_e32 v2, 10, v2
	v_mul_i32_i24_e32 v4, 0x400, v2
	v_sub_u32_e32 v3, v3, v4
	v_lshrrev_b32_e32 v4, 4, v3
	v_bitop3_b32 v4, v4, v3, 32 bitop3:0x6c
	v_ashrrev_i32_e32 v3, 31, v4
	v_lshrrev_b32_e32 v3, 26, v3
	v_add_u32_e32 v5, v4, v3
	v_lshlrev_b32_e32 v6, 3, v2
	v_ashrrev_i32_e32 v3, 6, v5
	v_and_b32_e32 v6, -16, v6
	v_add_u32_e32 v6, v3, v6
	v_and_b32_e32 v7, 3, v3
	s_mov_b32 s3, 0xfffe0
	v_lshrrev_b32_e32 v9, 2, v6
	v_lshlrev_b32_e32 v10, 1, v6
	v_and_b32_e32 v5, 0xc0, v5
	v_and_or_b32 v7, v6, s3, v7
	v_and_b32_e32 v9, 4, v9
	v_and_b32_e32 v10, 24, v10
	v_sub_u32_e32 v4, v4, v5
	v_mov_b32_e32 v13, 1
	v_or3_b32 v7, v7, v9, v10
	v_lshlrev_b32_e32 v9, 5, v2
	v_ashrrev_i16_sdwa v4, v13, sext(v4) dst_sel:DWORD dst_unused:UNUSED_PAD src0_sel:DWORD src1_sel:BYTE_0
	v_and_b32_e32 v9, 32, v9
	v_bfe_i32 v4, v4, 0, 16
	v_add_lshl_u32 v5, v9, v4, 1
	v_lshl_add_u32 v130, v7, 12, v5
	v_lshl_add_u32 v132, v6, 12, v5
	v_bfe_i32 v5, v8, 27, 1
	v_lshrrev_b32_e32 v5, 22, v5
	v_add_u32_e32 v5, v0, v5
	v_and_b32_e32 v5, 0xfffffc00, v5
	v_sub_u32_e32 v0, v0, v5
	v_lshrrev_b32_e32 v5, 4, v0
	v_ashrrev_i32_e32 v6, 31, v8
	v_bitop3_b32 v0, v5, v0, 32 bitop3:0x6c
	v_lshrrev_b32_e32 v6, 26, v6
	v_ashrrev_i32_e32 v5, 31, v0
	v_add_u32_e32 v6, v8, v6
	v_lshrrev_b32_e32 v5, 26, v5
	v_ashrrev_i32_e32 v6, 6, v6
	v_add_u32_e32 v7, v0, v5
	v_lshlrev_b32_e32 v9, 3, v6
	v_ashrrev_i32_e32 v5, 6, v7
	v_and_b32_e32 v9, -16, v9
	v_add_u32_e32 v9, v5, v9
	v_and_b32_e32 v10, 3, v5
	v_lshrrev_b32_e32 v11, 2, v9
	v_lshlrev_b32_e32 v12, 1, v9
	v_and_b32_e32 v7, 0xc0, v7
	s_ashr_i32 s1, s22, 6
	v_and_or_b32 v10, v9, s3, v10
	v_and_b32_e32 v11, 4, v11
	v_and_b32_e32 v12, 24, v12
	v_sub_u32_e32 v0, v0, v7
	s_ashr_i32 s0, s22, 8
	s_lshl_b32 s23, s1, 10
	v_or3_b32 v10, v10, v11, v12
	v_lshlrev_b32_e32 v11, 5, v6
	v_ashrrev_i16_sdwa v0, v13, sext(v0) dst_sel:DWORD dst_unused:UNUSED_PAD src0_sel:DWORD src1_sel:BYTE_0
	v_readlane_b32 s4, v252, 54
	v_readlane_b32 s3, v254, 10
	v_and_b32_e32 v11, 32, v11
	v_bfe_i32 v7, v0, 0, 16
	v_readlane_b32 s5, v252, 55
	s_add_u32 s18, s3, s4
	v_readlane_b32 s3, v254, 11
	v_add_lshl_u32 v11, v11, v7, 1
	s_addc_u32 s19, s3, s5
	s_add_i32 s24, s23, 0
	v_lshl_add_u32 v0, v10, 12, v11
	s_add_i32 m0, s24, 0x10000
	v_readlane_b32 s4, v252, 59
	global_load_lds_dwordx4 v0, s[18:19]
	s_add_i32 m0, s24, 0x12000
	v_lshl_add_u32 v134, v9, 12, v11
	global_load_lds_dwordx4 v130, s[18:19]
	s_mov_b32 m0, s24
	v_readlane_b32 s5, v252, 60
	s_add_i32 s25, s24, 0x2000
	s_nop 3
	global_load_lds_dwordx4 v134, s[4:5]
	s_mov_b32 m0, s25
	s_nop 0
	global_load_lds_dwordx4 v132, s[4:5]
	s_add_u32 s4, s18, 0x80000
	s_addc_u32 s5, s19, 0
	s_add_i32 m0, s24, 0x14000
	s_add_i32 s26, s24, 0x4000
	global_load_lds_dwordx4 v0, s[4:5]
	s_add_i32 m0, s24, 0x16000
	s_add_i32 s27, s24, 0x6000
	global_load_lds_dwordx4 v130, s[4:5]
	v_readlane_b32 s4, v252, 61
	s_mov_b32 m0, s26
	v_readlane_b32 s5, v252, 62
	s_cmp_lg_u32 s0, 1
	s_nop 3
	global_load_lds_dwordx4 v134, s[4:5]
	s_mov_b32 m0, s27
	s_nop 0
	global_load_lds_dwordx4 v132, s[4:5]
	s_cbranch_scc1 .LBB0_337
	s_barrier
	s_setprio 1

; #define PG8_WAIT_V(n) asm volatile("s_waitcnt vmcnt(" #n ")" ::: "memory")
; #define PG8_BAR __builtin_amdgcn_s_barrier()
; template <class Epi, class Sched>
; __device__ __forceinline__ void gemm_phase(LAS unsigned char* lds, const Gemm g, const Sched& S, const Epi& E) {
;     ...
;     PG8_WAIT_V(0);
;     if (wr == 0) PG8_BAR;
;     PG8_BAR;
.LBB0_361:
	s_barrier
	s_setprio 0

; #define PG8_STAGE(bufoff, gbase, voff) do { _Pragma("unroll") for (int _i = 0; _i < 2; ++_i) \
;         __builtin_amdgcn_global_load_lds((const unsigned*)((const char*)(gbase) + (voff)[_i]), (LAS unsigned*)(lds + (bufoff) + ldsw + _i * 8192), 16, 0, 0); } while (0)
; #define PG8_BAR __builtin_amdgcn_s_barrier()
; template <class Epi, class Sched>
; __device__ __forceinline__ void gemm_phase(LAS unsigned char* lds, const Gemm g, const Sched& S, const Epi& E) {
;     ...
;     for (int i = 0; i < 2; ++i) { int R, C; stage_rc(tid * 16 + i * 8192, R, C); const int Rb = Epi::PERM ? ((R & ~31) + perm32(R & 31)) : R;
;         voffA[i] = (unsigned)(R * K + C) * 2u; voffB[i] = (unsigned)(Rb * K + C) * 2u; }
;     const size_t kstep = (size_t)(BK * 2);
;     const size_t hstep = (size_t)HALF * K * 2;
;     const size_t tstep = 2 * hstep;
;     const unsigned ldsw = (unsigned)wid * 1024u;
;     const int aoff = lds_byte(wr * 64 + fr, fq * 8), boff = lds_byte(wc * 32 + fr, fq * 8);
;     ...
;     Unit cur, nxt; int ui = 0;
;     if (!S.next(0, cur)) return;
;     f32x4 acc[2][2][4][2];
; #pragma unroll
;     for (int a = 0; a < 2; ++a)
; #pragma unroll
;         for (int b = 0; b < 2; ++b)
; #pragma unroll
;             for (int m = 0; m < 4; ++m)
; #pragma unroll
;                 for (int n = 0; n < 2; ++n) acc[a][b][m][n] = (f32x4){0.f, 0.f, 0.f, 0.f};
;     bf16x8 At[4][2], B0[2][2], B1[2][2];
;     const char* cA = (const char*)g.A + (size_t)cur.pm * tstep; const char* cB = (const char*)g.Bt + (size_t)cur.pn * tstep;
;     S.a_ready(cur);
;     PG8_STAGE(PG8_SB(0, 0), cB, voffB); PG8_STAGE(PG8_SA(0, 0), cA, voffA); PG8_STAGE(PG8_SB(0, 1), cB + hstep, voffB); PG8_STAGE(PG8_SA(0, 1), cA + hstep, voffA);
;     if (wr == 1) PG8_BAR;
.LBB0_1115:
	v_cndmask_b32_e64 v0, 0, 1, s[0:1]
	v_cmp_ne_u32_e64 s[6:7], 1, v0
	s_andn2_b64 vcc, exec, s[0:1]
	s_cbranch_vccnz .LBB0_1159
	v_bfe_i32 v3, v2, 27, 1
	v_lshlrev_b32_e32 v6, 4, v2
	v_lshrrev_b32_e32 v3, 22, v3
	v_ashrrev_i32_e32 v0, 31, v2
	v_add_u32_e32 v3, v6, v3
	v_lshrrev_b32_e32 v0, 26, v0
	v_and_b32_e32 v3, 0xfffffc00, v3
	v_add_u32_e32 v0, v2, v0
	v_sub_u32_e32 v3, v6, v3
	v_ashrrev_i32_e32 v0, 6, v0
	v_lshrrev_b32_e32 v4, 4, v3
	v_bitop3_b32 v5, v4, v3, 32 bitop3:0x6c
	v_lshlrev_b32_e32 v3, 3, v0
	v_and_b32_e32 v4, 0xffff0, v3
	v_ashrrev_i32_e32 v3, 31, v5
	v_lshrrev_b32_e32 v3, 26, v3
	v_add_u32_e32 v7, v5, v3
	v_ashrrev_i32_e32 v3, 6, v7
	v_and_b32_e32 v7, 0xc0, v7
	v_add_u32_e32 v8, v3, v4
	v_lshlrev_b32_e32 v4, 5, v0
	v_sub_u32_e32 v5, v5, v7
	v_mov_b32_e32 v12, 1
	v_and_b32_e32 v4, 32, v4
	v_ashrrev_i16_sdwa v5, v12, sext(v5) dst_sel:DWORD dst_unused:UNUSED_PAD src0_sel:DWORD src1_sel:BYTE_0
	v_bfe_i32 v5, v5, 0, 16
	v_lshl_or_b32 v7, v8, 11, v4
	v_add_lshl_u32 v130, v7, v5, 1
	v_add_u32_e32 v7, 0x2000, v6
	v_ashrrev_i32_e32 v6, 31, v7
	v_lshrrev_b32_e32 v6, 22, v6
	v_add_u32_e32 v6, v7, v6
	v_ashrrev_i32_e32 v6, 10, v6
	v_mul_i32_i24_e32 v8, 0x400, v6
	v_sub_u32_e32 v7, v7, v8
	v_lshrrev_b32_e32 v8, 4, v7
	v_readlane_b32 s0, v254, 10
	v_bitop3_b32 v9, v8, v7, 32 bitop3:0x6c
	v_lshlrev_b32_e32 v7, 3, v6
	s_add_u32 s28, s0, 0x1c00000
	v_readlane_b32 s0, v254, 11
	v_and_b32_e32 v8, 0xffff0, v7
	v_ashrrev_i32_e32 v7, 31, v9
	s_addc_u32 s29, s0, 0
	v_lshrrev_b32_e32 v7, 26, v7
	s_ashr_i32 s1, s27, 6
	s_ashr_i32 s17, s16, 31
	s_ashr_i32 s15, s14, 31
	s_ashr_i32 s0, s27, 8
	v_add_u32_e32 v10, v9, v7
	s_lshl_b32 s30, s1, 10
	s_lshl_b64 s[4:5], s[16:17], 20
	s_lshl_b64 s[8:9], s[14:15], 20
	v_ashrrev_i32_e32 v7, 6, v10
	v_and_b32_e32 v10, 0xc0, v10
	s_add_u32 s20, s28, s8
	v_add_u32_e32 v11, v7, v8
	v_lshlrev_b32_e32 v8, 5, v6
	v_sub_u32_e32 v9, v9, v10
	s_addc_u32 s21, s29, s9
	s_add_i32 s31, s30, 0
	v_and_b32_e32 v8, 32, v8
	v_ashrrev_i16_sdwa v9, v12, sext(v9) dst_sel:DWORD dst_unused:UNUSED_PAD src0_sel:DWORD src1_sel:BYTE_0
	s_add_i32 m0, s31, 0x10000
	v_bfe_i32 v9, v9, 0, 16
	v_lshl_or_b32 v10, v11, 11, v8
	global_load_lds_dwordx4 v130, s[20:21]
	s_add_i32 m0, s31, 0x12000
	v_add_lshl_u32 v132, v10, v9, 1
	s_add_u32 s18, s56, s4
	global_load_lds_dwordx4 v132, s[20:21]
	s_addc_u32 s19, s57, s5
	s_mov_b32 m0, s31
	s_add_i32 s34, s31, 0x2000
	global_load_lds_dwordx4 v130, s[18:19]
	s_mov_b32 m0, s34
	s_add_u32 s4, s20, 0x80000
	global_load_lds_dwordx4 v132, s[18:19]
	s_addc_u32 s5, s21, 0
	s_add_i32 m0, s31, 0x14000
	s_nop 0
	global_load_lds_dwordx4 v130, s[4:5]
	s_add_i32 m0, s31, 0x16000
	s_nop 0
	global_load_lds_dwordx4 v132, s[4:5]
	s_add_u32 s4, s18, 0x80000
	s_addc_u32 s5, s19, 0
	s_add_i32 s35, s31, 0x4000
	s_mov_b32 m0, s35
	s_add_i32 s36, s31, 0x6000
	global_load_lds_dwordx4 v130, s[4:5]
	s_mov_b32 m0, s36
	s_cmp_lg_u32 s0, 1
	global_load_lds_dwordx4 v132, s[4:5]
	s_cbranch_scc1 .LBB0_1118
	s_barrier
	s_setprio 1

; #define PG8_STAGE(bufoff, gbase, voff) do { _Pragma("unroll") for (int _i = 0; _i < 2; ++_i) \
;         __builtin_amdgcn_global_load_lds((const unsigned*)((const char*)(gbase) + (voff)[_i]), (LAS unsigned*)(lds + (bufoff) + ldsw + _i * 8192), 16, 0, 0); } while (0)
; #define PG8_BAR __builtin_amdgcn_s_barrier()
;     __host__ __device__ bool next(int i, Unit& u) const {
;         const long L = (long)i * G + c; if (L >= nwg) return false;
;         int wgid = (int)L; { const int q = nwg / NXCD, r = nwg % NXCD, xcd = wgid % NXCD, off = wgid / NXCD; wgid = (xcd < r ? xcd * (q + 1) : r * (q + 1) + (xcd - r) * q) + off; }
;         const int nig = wgm * nN, gid = wgid / nig, fm = gid * wgm, gsz = (nM - fm) < wgm ? (nM - fm) : wgm;
;         u.pm = fm + ((wgid % nig) % gsz); u.pn = (wgid % nig) / gsz; return true;
;     }
; template <class Epi, class Sched>
; __device__ __forceinline__ void gemm_phase(LAS unsigned char* lds, const Gemm g, const Sched& S, const Epi& E) {
;     ...
;     for (int i = 0; i < 2; ++i) { int R, C; stage_rc(tid * 16 + i * 8192, R, C); const int Rb = Epi::PERM ? ((R & ~31) + perm32(R & 31)) : R;
;         voffA[i] = (unsigned)(R * K + C) * 2u; voffB[i] = (unsigned)(Rb * K + C) * 2u; }
;     const size_t kstep = (size_t)(BK * 2);
;     const size_t hstep = (size_t)HALF * K * 2;
;     const size_t tstep = 2 * hstep;
;     const unsigned ldsw = (unsigned)wid * 1024u;
;     const int aoff = lds_byte(wr * 64 + fr, fq * 8), boff = lds_byte(wc * 32 + fr, fq * 8);
;     ...
;     Unit cur, nxt; int ui = 0;
;     if (!S.next(0, cur)) return;
;     f32x4 acc[2][2][4][2];
; #pragma unroll
;     for (int a = 0; a < 2; ++a)
; #pragma unroll
;         for (int b = 0; b < 2; ++b)
; #pragma unroll
;             for (int m = 0; m < 4; ++m)
; #pragma unroll
;                 for (int n = 0; n < 2; ++n) acc[a][b][m][n] = (f32x4){0.f, 0.f, 0.f, 0.f};
;     bf16x8 At[4][2], B0[2][2], B1[2][2];
;     const char* cA = (const char*)g.A + (size_t)cur.pm * tstep; const char* cB = (const char*)g.Bt + (size_t)cur.pn * tstep;
;     S.a_ready(cur);
;     PG8_STAGE(PG8_SB(0, 0), cB, voffB); PG8_STAGE(PG8_SA(0, 0), cA, voffA); PG8_STAGE(PG8_SB(0, 1), cB + hstep, voffB); PG8_STAGE(PG8_SA(0, 1), cA + hstep, voffA);
;     if (wr == 1) PG8_BAR;
.LBB0_1272:
	s_or_b64 exec, exec, s[0:1]
	v_readlane_b32 s5, v253, 63
	s_lshr_b32 s4, s5, 3
	v_mov_b32_e32 v8, v170
	s_waitcnt lgkmcnt(0)
	s_barrier
	s_cmp_ge_i32 s54, s4
	v_readfirstlane_b32 s27, v8
	s_cbranch_scc1 .LBB0_1284
	v_lshlrev_b32_e32 v0, 4, v8
	v_add_u32_e32 v3, 0x2000, v0
	v_ashrrev_i32_e32 v2, 31, v3
	v_lshrrev_b32_e32 v2, 22, v2
	v_add_u32_e32 v2, v3, v2
	v_ashrrev_i32_e32 v2, 10, v2
	v_mul_i32_i24_e32 v4, 0x400, v2
	v_sub_u32_e32 v3, v3, v4
	v_lshrrev_b32_e32 v4, 4, v3
	v_bitop3_b32 v4, v4, v3, 32 bitop3:0x6c
	v_ashrrev_i32_e32 v3, 31, v4
	v_lshrrev_b32_e32 v3, 26, v3
	v_add_u32_e32 v5, v4, v3
	v_lshlrev_b32_e32 v6, 3, v2
	v_ashrrev_i32_e32 v3, 6, v5
	v_and_b32_e32 v6, -16, v6
	v_add_u32_e32 v6, v3, v6
	v_and_b32_e32 v7, 3, v3
	s_mov_b32 s3, 0xfffe0
	v_lshrrev_b32_e32 v9, 2, v6
	v_lshlrev_b32_e32 v10, 1, v6
	v_and_b32_e32 v5, 0xc0, v5
	v_and_or_b32 v7, v6, s3, v7
	v_and_b32_e32 v9, 4, v9
	v_and_b32_e32 v10, 24, v10
	v_sub_u32_e32 v4, v4, v5
	v_mov_b32_e32 v13, 1
	v_or3_b32 v7, v7, v9, v10
	v_lshlrev_b32_e32 v9, 5, v2
	v_ashrrev_i16_sdwa v4, v13, sext(v4) dst_sel:DWORD dst_unused:UNUSED_PAD src0_sel:DWORD src1_sel:BYTE_0
	v_and_b32_e32 v9, 32, v9
	v_bfe_i32 v4, v4, 0, 16
	v_add_lshl_u32 v5, v9, v4, 1
	v_lshl_add_u32 v130, v7, 12, v5
	v_lshl_add_u32 v132, v6, 12, v5
	v_bfe_i32 v5, v8, 27, 1
	v_lshrrev_b32_e32 v5, 22, v5
	v_add_u32_e32 v5, v0, v5
	v_and_b32_e32 v5, 0xfffffc00, v5
	v_sub_u32_e32 v0, v0, v5
	v_lshrrev_b32_e32 v5, 4, v0
	v_ashrrev_i32_e32 v6, 31, v8
	v_bitop3_b32 v0, v5, v0, 32 bitop3:0x6c
	v_lshrrev_b32_e32 v6, 26, v6
	v_readlane_b32 s0, v254, 10
	v_ashrrev_i32_e32 v5, 31, v0
	v_add_u32_e32 v6, v8, v6
	s_add_u32 s28, s0, 0x2400000
	v_readlane_b32 s0, v254, 11
	v_lshrrev_b32_e32 v5, 26, v5
	v_ashrrev_i32_e32 v6, 6, v6
	s_addc_u32 s29, s0, 0
	s_ashr_i32 s0, s27, 6
	v_add_u32_e32 v7, v0, v5
	v_lshlrev_b32_e32 v9, 3, v6
	s_lshr_b32 s31, s5, 6
	v_readlane_b32 s8, v252, 47
	s_ashr_i32 s1, s27, 8
	s_lshl_b32 s30, s0, 10
	v_ashrrev_i32_e32 v5, 6, v7
	v_and_b32_e32 v9, -16, v9
	s_or_b32 s34, s31, 1
	v_readlane_b32 s9, v252, 48
	v_add_u32_e32 v9, v5, v9
	v_and_b32_e32 v10, 3, v5
	s_and_b64 s[8:9], s[8:9], exec
	v_and_or_b32 v10, v9, s3, v10
	s_cselect_b32 s3, s34, s31
	v_readlane_b32 s5, v253, 2
	s_mul_i32 s3, s3, s5
	v_readlane_b32 s5, v252, 49
	s_add_i32 s3, s3, s5
	s_ashr_i32 s5, s3, 31
	s_lshr_b32 s5, s5, 24
	s_add_i32 s5, s3, s5
	s_ashr_i32 s8, s5, 8
	s_lshl_b32 s8, s8, 3
	s_sub_i32 s9, s26, s8
	v_lshrrev_b32_e32 v11, 2, v9
	v_lshlrev_b32_e32 v12, 1, v9
	s_min_i32 s9, s9, 8
	v_and_b32_e32 v11, 4, v11
	v_and_b32_e32 v12, 24, v12
	v_and_b32_e32 v7, 0xc0, v7
	s_abs_i32 s10, s9
	v_or3_b32 v10, v10, v11, v12
	v_sub_u32_e32 v0, v0, v7
	v_cvt_f32_u32_e32 v12, s10
	v_lshlrev_b32_e32 v11, 5, v6
	v_ashrrev_i16_sdwa v0, v13, sext(v0) dst_sel:DWORD dst_unused:UNUSED_PAD src0_sel:DWORD src1_sel:BYTE_0
	v_and_b32_e32 v11, 32, v11
	v_bfe_i32 v7, v0, 0, 16
	v_add_lshl_u32 v11, v11, v7, 1
	v_lshl_add_u32 v134, v9, 12, v11
	v_rcp_iflag_f32_e32 v9, v12
	s_sub_i32 s12, 0, s10
	s_and_b32 s5, s5, 0xffffff00
	s_sub_i32 s3, s3, s5
	v_mul_f32_e32 v9, 0x4f7ffffe, v9
	v_cvt_u32_f32_e32 v9, v9
	s_abs_i32 s11, s3
	s_xor_b32 s5, s3, s9
	s_ashr_i32 s5, s5, 31
	v_readfirstlane_b32 s13, v9
	s_mul_i32 s12, s12, s13
	s_mul_hi_u32 s12, s13, s12
	s_add_i32 s13, s13, s12
	s_mul_hi_u32 s12, s11, s13
	s_mul_i32 s13, s12, s10
	s_sub_i32 s11, s11, s13
	s_add_i32 s13, s12, 1
	s_sub_i32 s14, s11, s10
	s_cmp_ge_u32 s11, s10
	s_cselect_b32 s12, s13, s12
	s_cselect_b32 s11, s14, s11
	s_add_i32 s13, s12, 1
	s_cmp_ge_u32 s11, s10
	s_cselect_b32 s10, s13, s12
	s_xor_b32 s10, s10, s5
	s_sub_i32 s16, s10, s5
	s_mul_i32 s5, s16, s9
	s_sub_i32 s3, s3, s5
	s_add_i32 s18, s8, s3
	s_ashr_i32 s19, s18, 31
	s_ashr_i32 s17, s16, 31
	s_lshl_b64 s[8:9], s[18:19], 20
	s_lshl_b64 s[10:11], s[16:17], 20
	s_add_u32 s22, s28, s10
	s_addc_u32 s23, s29, s11
	s_add_i32 s17, s30, 0
	v_lshl_add_u32 v0, v10, 12, v11
	s_add_i32 m0, s17, 0x10000
	s_nop 0
	global_load_lds_dwordx4 v0, s[22:23]
	s_add_i32 m0, s17, 0x12000
	s_add_u32 s20, s56, s8
	global_load_lds_dwordx4 v130, s[22:23]
	s_addc_u32 s21, s57, s9
	s_mov_b32 m0, s17
	s_add_i32 s19, s17, 0x2000
	global_load_lds_dwordx4 v134, s[20:21]
	s_mov_b32 m0, s19
	s_add_u32 s8, s22, 0x80000
	global_load_lds_dwordx4 v132, s[20:21]
	s_addc_u32 s9, s23, 0
	s_add_i32 m0, s17, 0x14000
	s_nop 0
	global_load_lds_dwordx4 v0, s[8:9]
	s_add_i32 m0, s17, 0x16000
	s_nop 0
	global_load_lds_dwordx4 v130, s[8:9]
	s_add_u32 s8, s20, 0x80000
	s_addc_u32 s9, s21, 0
	s_add_i32 s35, s17, 0x4000
	s_mov_b32 m0, s35
	s_add_i32 s36, s17, 0x6000
	global_load_lds_dwordx4 v134, s[8:9]
	s_mov_b32 m0, s36
	s_cmp_lg_u32 s1, 1
	global_load_lds_dwordx4 v132, s[8:9]
	s_cbranch_scc1 .LBB0_1275
	s_barrier
	s_setprio 1

; #define PG8_WAIT_V(n) asm volatile("s_waitcnt vmcnt(" #n ")" ::: "memory")
; #define PG8_BAR __builtin_amdgcn_s_barrier()
; template <class Epi, class Sched>
; __device__ __forceinline__ void gemm_phase(LAS unsigned char* lds, const Gemm g, const Sched& S, const Epi& E) {
;     ...
;     PG8_WAIT_V(0);
;     if (wr == 0) PG8_BAR;
;     PG8_BAR;
.LBB0_1283:
	v_mov_b32_e32 v170, v219
	s_barrier
	s_setprio 0

; #define PG8_STAGE(bufoff, gbase, voff) do { _Pragma("unroll") for (int _i = 0; _i < 2; ++_i) \
;         __builtin_amdgcn_global_load_lds((const unsigned*)((const char*)(gbase) + (voff)[_i]), (LAS unsigned*)(lds + (bufoff) + ldsw + _i * 8192), 16, 0, 0); } while (0)
; #define PG8_BAR __builtin_amdgcn_s_barrier()
;     __host__ __device__ bool next(int i, Unit& u) const {
;         const long L = (long)i * G + c; if (L >= nwg) return false;
;         int wgid = (int)L; { const int q = nwg / NXCD, r = nwg % NXCD, xcd = wgid % NXCD, off = wgid / NXCD; wgid = (xcd < r ? xcd * (q + 1) : r * (q + 1) + (xcd - r) * q) + off; }
;         const int nig = wgm * nN, gid = wgid / nig, fm = gid * wgm, gsz = (nM - fm) < wgm ? (nM - fm) : wgm;
;         u.pm = fm + ((wgid % nig) % gsz); u.pn = (wgid % nig) / gsz; return true;
;     }
; template <class Epi, class Sched>
; __device__ __forceinline__ void gemm_phase(LAS unsigned char* lds, const Gemm g, const Sched& S, const Epi& E) {
;     ...
;     for (int i = 0; i < 2; ++i) { int R, C; stage_rc(tid * 16 + i * 8192, R, C); const int Rb = Epi::PERM ? ((R & ~31) + perm32(R & 31)) : R;
;         voffA[i] = (unsigned)(R * K + C) * 2u; voffB[i] = (unsigned)(Rb * K + C) * 2u; }
;     const size_t kstep = (size_t)(BK * 2);
;     const size_t hstep = (size_t)HALF * K * 2;
;     const size_t tstep = 2 * hstep;
;     const unsigned ldsw = (unsigned)wid * 1024u;
;     const int aoff = lds_byte(wr * 64 + fr, fq * 8), boff = lds_byte(wc * 32 + fr, fq * 8);
;     ...
;     Unit cur, nxt; int ui = 0;
;     if (!S.next(0, cur)) return;
;     f32x4 acc[2][2][4][2];
; #pragma unroll
;     for (int a = 0; a < 2; ++a)
; #pragma unroll
;         for (int b = 0; b < 2; ++b)
; #pragma unroll
;             for (int m = 0; m < 4; ++m)
; #pragma unroll
;                 for (int n = 0; n < 2; ++n) acc[a][b][m][n] = (f32x4){0.f, 0.f, 0.f, 0.f};
;     bf16x8 At[4][2], B0[2][2], B1[2][2];
;     const char* cA = (const char*)g.A + (size_t)cur.pm * tstep; const char* cB = (const char*)g.Bt + (size_t)cur.pn * tstep;
;     S.a_ready(cur);
;     PG8_STAGE(PG8_SB(0, 0), cB, voffB); PG8_STAGE(PG8_SA(0, 0), cA, voffA); PG8_STAGE(PG8_SB(0, 1), cB + hstep, voffB); PG8_STAGE(PG8_SA(0, 1), cA + hstep, voffA);
;     if (wr == 1) PG8_BAR;
.LBB0_1336:
	s_or_b64 exec, exec, s[0:1]
	v_mov_b32_e32 v10, v170
	s_waitcnt lgkmcnt(0)
	s_barrier
	s_and_b64 vcc, exec, s[6:7]
	v_readfirstlane_b32 s24, v10
	s_cbranch_vccnz .LBB0_1348
	v_lshlrev_b32_e32 v0, 4, v10
	v_add_u32_e32 v3, 0x2000, v0
	v_ashrrev_i32_e32 v2, 31, v3
	v_lshrrev_b32_e32 v2, 22, v2
	v_add_u32_e32 v2, v3, v2
	v_ashrrev_i32_e32 v2, 10, v2
	v_mul_i32_i24_e32 v4, 0x400, v2
	v_sub_u32_e32 v3, v3, v4
	v_lshrrev_b32_e32 v4, 4, v3
	v_bitop3_b32 v5, v4, v3, 32 bitop3:0x6c
	v_ashrrev_i32_e32 v3, 31, v5
	v_readlane_b32 s0, v254, 10
	v_lshrrev_b32_e32 v3, 26, v3
	s_add_u32 s25, s0, 0x4400000
	v_readlane_b32 s0, v254, 11
	v_add_u32_e32 v6, v5, v3
	v_readlane_b32 s3, v253, 3
	s_addc_u32 s27, s0, 0
	v_ashrrev_i32_e32 v3, 6, v6
	v_and_b32_e32 v6, 0xc0, v6
	s_or_b32 s3, s26, s3
	v_readlane_b32 s4, v253, 2
	v_lshlrev_b32_e32 v4, 3, v2
	v_sub_u32_e32 v5, v5, v6
	v_bfe_i32 v6, v10, 27, 1
	s_mul_i32 s3, s3, s4
	v_readlane_b32 s4, v252, 49
	v_and_b32_e32 v4, 0x3fff0, v4
	v_lshrrev_b32_e32 v6, 22, v6
	s_add_i32 s3, s3, s4
	v_add_u32_e32 v7, v3, v4
	v_lshlrev_b32_e32 v4, 5, v2
	v_mov_b32_e32 v13, 1
	v_add_u32_e32 v6, v0, v6
	s_ashr_i32 s4, s3, 31
	v_and_b32_e32 v4, 32, v4
	v_ashrrev_i16_sdwa v5, v13, sext(v5) dst_sel:DWORD dst_unused:UNUSED_PAD src0_sel:DWORD src1_sel:BYTE_0
	v_and_b32_e32 v6, 0xfffffc00, v6
	s_lshr_b32 s4, s4, 28
	v_lshl_or_b32 v7, v7, 13, v4
	v_bfe_i32 v5, v5, 0, 16
	v_sub_u32_e32 v0, v0, v6
	s_add_i32 s4, s3, s4
	v_add_lshl_u32 v130, v7, v5, 1
	v_lshrrev_b32_e32 v6, 4, v0
	v_ashrrev_i32_e32 v7, 31, v10
	s_ashr_i32 s5, s4, 4
	v_bitop3_b32 v0, v6, v0, 32 bitop3:0x6c
	v_lshrrev_b32_e32 v7, 26, v7
	s_lshl_b32 s5, s5, 1
	v_ashrrev_i32_e32 v6, 31, v0
	v_add_u32_e32 v7, v10, v7
	s_sub_i32 s6, s26, s5
	v_lshrrev_b32_e32 v6, 26, v6
	v_ashrrev_i32_e32 v7, 6, v7
	s_min_i32 s6, s6, 2
	v_add_u32_e32 v9, v0, v6
	v_lshlrev_b32_e32 v8, 3, v7
	s_abs_i32 s7, s6
	v_ashrrev_i32_e32 v6, 6, v9
	v_and_b32_e32 v8, 0x3fff0, v8
	v_and_b32_e32 v9, 0xc0, v9
	v_cvt_f32_u32_e32 v12, s7
	v_add_u32_e32 v11, v6, v8
	v_lshlrev_b32_e32 v8, 5, v7
	v_sub_u32_e32 v0, v0, v9
	v_and_b32_e32 v8, 32, v8
	v_ashrrev_i16_sdwa v0, v13, sext(v0) dst_sel:DWORD dst_unused:UNUSED_PAD src0_sel:DWORD src1_sel:BYTE_0
	v_lshl_or_b32 v11, v11, 13, v8
	v_bfe_i32 v9, v0, 0, 16
	v_add_lshl_u32 v0, v11, v9, 1
	v_rcp_iflag_f32_e32 v11, v12
	s_sub_i32 s9, 0, s7
	s_and_b32 s4, s4, -16
	s_sub_i32 s3, s3, s4
	v_mul_f32_e32 v11, 0x4f7ffffe, v11
	v_cvt_u32_f32_e32 v11, v11
	s_abs_i32 s8, s3
	s_ashr_i32 s0, s24, 6
	s_xor_b32 s4, s3, s6
	v_readfirstlane_b32 s10, v11
	s_mul_i32 s9, s9, s10
	s_mul_hi_u32 s9, s10, s9
	s_add_i32 s10, s10, s9
	s_mul_hi_u32 s9, s8, s10
	s_mul_i32 s10, s9, s7
	s_sub_i32 s8, s8, s10
	s_ashr_i32 s1, s24, 8
	s_lshl_b32 s28, s0, 10
	s_ashr_i32 s4, s4, 31
	s_add_i32 s10, s9, 1
	s_sub_i32 s11, s8, s7
	s_cmp_ge_u32 s8, s7
	s_cselect_b32 s9, s10, s9
	s_cselect_b32 s8, s11, s8
	s_add_i32 s10, s9, 1
	s_cmp_ge_u32 s8, s7
	s_cselect_b32 s7, s10, s9
	s_xor_b32 s7, s7, s4
	s_sub_i32 s12, s7, s4
	s_mul_i32 s4, s12, s6
	s_sub_i32 s3, s3, s4
	s_add_i32 s14, s5, s3
	s_ashr_i32 s15, s14, 31
	s_ashr_i32 s13, s12, 31
	s_lshl_b64 s[4:5], s[14:15], 22
	s_lshl_b64 s[6:7], s[12:13], 22
	s_add_u32 s18, s25, s6
	s_addc_u32 s19, s27, s7
	s_add_i32 s13, s28, 0
	s_add_i32 m0, s13, 0x10000
	s_nop 0
	global_load_lds_dwordx4 v0, s[18:19]
	s_add_i32 m0, s13, 0x12000
	s_add_u32 s16, s58, s4
	global_load_lds_dwordx4 v130, s[18:19]
	s_addc_u32 s17, s59, s5
	s_mov_b32 m0, s13
	s_add_i32 s15, s13, 0x2000
	global_load_lds_dwordx4 v0, s[16:17]
	s_mov_b32 m0, s15
	s_add_u32 s4, s18, 0x200000
	global_load_lds_dwordx4 v130, s[16:17]
	s_addc_u32 s5, s19, 0
	s_add_i32 m0, s13, 0x14000
	s_nop 0
	global_load_lds_dwordx4 v0, s[4:5]
	s_add_i32 m0, s13, 0x16000
	s_nop 0
	global_load_lds_dwordx4 v130, s[4:5]
	s_add_u32 s4, s16, 0x200000
	s_addc_u32 s5, s17, 0
	s_add_i32 s29, s13, 0x4000
	s_mov_b32 m0, s29
	s_add_i32 s30, s13, 0x6000
	global_load_lds_dwordx4 v0, s[4:5]
	s_mov_b32 m0, s30
	s_cmp_lg_u32 s1, 1
	global_load_lds_dwordx4 v130, s[4:5]
	s_cbranch_scc1 .LBB0_1339
	s_barrier
	s_setprio 1
